# as v167 but the same-XCD panel-poll paths execute no invalidate at all (no line of the polled data can be in this CU's L1 since its last invalidate)
# speedup vs baseline: 1.0026x; 1.0026x over previous
.Lmy_pw1_l1:
	s_nop 0
	s_nop 0
